# SGU V^T tile requested at the start of the phase, published by the context chain's barriers (no wait, no barrier in the SGU task)
# speedup vs baseline: 1.0222x; 1.0042x over previous
.Lsp3_entry:
	s_cmpk_ge_u32 s63, 0xc0
	s_cbranch_scc1 .Lsgu_pre_skip
	v_and_b32_e32 v125, 63, v206
	v_lshrrev_b32_e32 v124, 6, v206
	v_and_b32_e32 v120, 15, v125
	v_lshrrev_b32_e32 v121, 4, v125
	v_readfirstlane_b32 s40, v124
	s_lshr_b32 s41, s63, 2
	s_and_b32 s42, s63, 3
	s_lshl_b32 s100, s41, 8
	s_lshl_b32 s101, s42, 6
	s_add_u32 s100, s100, s101
	s_lshl_b32 s100, s100, 8
	s_add_u32 s100, s100, 0xc784000
	s_add_u32 s46, s96, s100
	s_addc_u32 s47, s97, 0
	s_and_b32 s100, s40, 3
	s_lshl_b32 s100, s100, 2
	v_add_u32_e32 v126, s100, v121
	v_xor_b32_e32 v126, v126, v120
	v_lshlrev_b32_e32 v126, 4, v126
	v_lshl_add_u32 v126, v121, 8, v126
	s_lshl_b32 s101, s40, 10
	s_add_u32 s46, s46, s101
	s_addc_u32 s47, s47, 0
	s_add_u32 m0, s101, 0x23010
	s_nop 0
	global_load_lds_dwordx4 v126, s[46:47]
	s_add_u32 s46, s46, 0x2000
	s_addc_u32 s47, s47, 0
	s_add_u32 m0, s101, 0x25010
	s_nop 0
	global_load_lds_dwordx4 v126, s[46:47]

.Lsp3_e0:
	s_cmpk_ge_u32 s63, 0xc0
	s_cbranch_scc1 .Lsp3_e2
	v_and_b32_e32 v125, 63, v206
	v_lshrrev_b32_e32 v124, 6, v206
	v_and_b32_e32 v120, 15, v125
	v_readfirstlane_b32 s40, v124
	v_lshrrev_b32_e32 v121, 4, v125
	s_lshr_b32 s41, s63, 2
	s_and_b32 s42, s63, 3
	v_lshlrev_b32_e32 v122, 8, v120
	v_lshl_add_u32 v122, v121, 4, v122
	s_lshl_b32 s43, s36, 2
	s_add_u32 s43, s43, s42
	s_lshl_b32 s100, s43, 7
	s_lshl_b32 s101, s40, 4
	s_add_u32 s100, s100, s101
	s_lshl_b32 s100, s100, 8
	s_add_u32 s100, s100, 0x2dc0000
	s_add_u32 s44, s96, s100
	s_addc_u32 s45, s97, 0
	global_load_dwordx4 v[4:7], v122, s[44:45]
	global_load_dwordx4 v[8:11], v122, s[44:45] offset:64
	global_load_dwordx4 v[12:15], v122, s[44:45] offset:128
	global_load_dwordx4 v[16:19], v122, s[44:45] offset:192
	s_lshl_b32 s100, s41, 8
	s_lshl_b32 s101, s42, 6
	s_add_u32 s100, s100, s101
	s_lshl_b32 s100, s100, 8
	s_add_u32 s100, s100, 0xc784000
	s_add_u32 s46, s96, s100
	s_addc_u32 s47, s97, 0
	v_add_u32_e32 v127, 0, v121
	v_xor_b32_e32 v127, v127, v120
	v_lshlrev_b32_e32 v127, 4, v127
	v_lshl_add_u32 v127, v120, 8, v127
	v_add_u32_e32 v127, 0x23010, v127
	v_add_u32_e32 v128, 4, v121
	v_xor_b32_e32 v128, v128, v120
	v_lshlrev_b32_e32 v128, 4, v128
	v_lshl_add_u32 v128, v120, 8, v128
	v_add_u32_e32 v128, 0x23010, v128
	v_add_u32_e32 v129, 8, v121
	v_xor_b32_e32 v129, v129, v120
	v_lshlrev_b32_e32 v129, 4, v129
	v_lshl_add_u32 v129, v120, 8, v129
	v_add_u32_e32 v129, 0x23010, v129
	v_add_u32_e32 v130, 12, v121
	v_xor_b32_e32 v130, v130, v120
	v_lshlrev_b32_e32 v130, 4, v130
	v_lshl_add_u32 v130, v120, 8, v130
	v_add_u32_e32 v130, 0x23010, v130
	v_readlane_b32 s48, v237, 33
	v_readlane_b32 s49, v237, 34
	s_lshl_b32 s100, s43, 9
	s_lshl_b32 s101, s40, 6
	s_add_u32 s100, s100, s101
	s_add_u32 s48, s48, s100
	s_addc_u32 s49, s49, 0
	v_lshlrev_b32_e32 v125, 4, v121
	s_nop 0
	global_load_dwordx4 v[100:103], v125, s[48:49]
	s_lshl_b32 s100, s41, 7
	s_lshl_b32 s101, s40, 4
	s_add_u32 s100, s100, s101
	s_mul_i32 s50, s100, 0x2440
	s_lshl_b32 s101, s42, 8
	s_add_u32 s50, s50, s101
	s_add_u32 s50, s50, 0x3a25840
	s_add_u32 s52, s96, s50
	s_addc_u32 s53, s97, 0
	v_mul_u32_u24_e32 v123, 0x9100, v121
	v_lshl_add_u32 v123, v120, 2, v123
	global_load_dword v104, v123, s[52:53]
	global_load_dword v105, v123, s[52:53] offset:64
	global_load_dword v106, v123, s[52:53] offset:128
	global_load_dword v107, v123, s[52:53] offset:192
	v_add_u32_e32 v125, 0x2440, v123
	global_load_dword v108, v125, s[52:53]
	global_load_dword v109, v125, s[52:53] offset:64
	global_load_dword v110, v125, s[52:53] offset:128
	global_load_dword v111, v125, s[52:53] offset:192
	v_add_u32_e32 v125, 0x4880, v123
	global_load_dword v112, v125, s[52:53]
	global_load_dword v113, v125, s[52:53] offset:64
	global_load_dword v114, v125, s[52:53] offset:128
	global_load_dword v115, v125, s[52:53] offset:192
	v_add_u32_e32 v125, 0x6cc0, v123
	global_load_dword v116, v125, s[52:53]
	global_load_dword v117, v125, s[52:53] offset:64
	global_load_dword v118, v125, s[52:53] offset:128
	global_load_dword v119, v125, s[52:53] offset:192
	s_lshl_b32 s50, s100, 11
	s_lshl_b32 s101, s42, 7
	s_add_u32 s50, s50, s101
	s_add_u32 s50, s50, 0x7084400
	s_add_u32 s54, s96, s50
	s_addc_u32 s55, s97, 0
	v_lshlrev_b32_e32 v124, 13, v121
	v_lshl_add_u32 v124, v120, 1, v124
	ds_read_b128 v[20:23], v127 offset:0
	ds_read_b128 v[36:39], v128 offset:0
	ds_read_b128 v[52:55], v129 offset:0
	ds_read_b128 v[68:71], v130 offset:0
	ds_read_b128 v[24:27], v127 offset:4096
	ds_read_b128 v[40:43], v128 offset:4096
	ds_read_b128 v[56:59], v129 offset:4096
	ds_read_b128 v[72:75], v130 offset:4096
	ds_read_b128 v[28:31], v127 offset:8192
	ds_read_b128 v[44:47], v128 offset:8192
	ds_read_b128 v[60:63], v129 offset:8192
	ds_read_b128 v[76:79], v130 offset:8192
	s_waitcnt lgkmcnt(8)
	ds_read_b128 v[32:35], v127 offset:12288
	ds_read_b128 v[48:51], v128 offset:12288
	ds_read_b128 v[64:67], v129 offset:12288
	ds_read_b128 v[80:83], v130 offset:12288
	s_waitcnt vmcnt(17) lgkmcnt(0)
	v_mfma_f32_16x16x32_bf16 v[84:87], v[4:7], v[20:23], 0
	v_mfma_f32_16x16x32_bf16 v[88:91], v[4:7], v[24:27], 0
	v_mfma_f32_16x16x32_bf16 v[92:95], v[4:7], v[28:31], 0
	v_mfma_f32_16x16x32_bf16 v[96:99], v[4:7], v[32:35], 0
	v_mfma_f32_16x16x32_bf16 v[84:87], v[8:11], v[36:39], v[84:87]
	v_mfma_f32_16x16x32_bf16 v[88:91], v[8:11], v[40:43], v[88:91]
	v_mfma_f32_16x16x32_bf16 v[92:95], v[8:11], v[44:47], v[92:95]
	v_mfma_f32_16x16x32_bf16 v[96:99], v[8:11], v[48:51], v[96:99]
	v_mfma_f32_16x16x32_bf16 v[84:87], v[12:15], v[52:55], v[84:87]
	v_mfma_f32_16x16x32_bf16 v[88:91], v[12:15], v[56:59], v[88:91]
	v_mfma_f32_16x16x32_bf16 v[92:95], v[12:15], v[60:63], v[92:95]
	v_mfma_f32_16x16x32_bf16 v[96:99], v[12:15], v[64:67], v[96:99]
	v_mfma_f32_16x16x32_bf16 v[84:87], v[16:19], v[68:71], v[84:87]
	v_mfma_f32_16x16x32_bf16 v[88:91], v[16:19], v[72:75], v[88:91]
	v_mfma_f32_16x16x32_bf16 v[92:95], v[16:19], v[76:79], v[92:95]
	v_mfma_f32_16x16x32_bf16 v[96:99], v[16:19], v[80:83], v[96:99]
	s_waitcnt vmcnt(0)
	s_nop 4
	v_mul_f32_e32 v126, 0x3d372713, v104
	v_mul_f32_e32 v126, v104, v126
	v_fma_f32 v126, v104, v126, v104
	v_mul_f32_e32 v126, 0x3f4c422a, v126
	v_add_f32_e32 v126, v126, v126
	v_mul_f32_e32 v126, 0x3fb8aa3b, v126
	v_exp_f32_e32 v126, v126
	v_mul_f32_e32 v127, 0.5, v104
	v_add_f32_e32 v126, 1.0, v126
	v_div_scale_f32 v128, s[100:101], v126, v126, 2.0
	v_rcp_f32_e32 v129, v128
	s_nop 0
	v_fma_f32 v130, -v128, v129, 1.0
	v_fmac_f32_e32 v129, v130, v129
	v_div_scale_f32 v130, vcc, 2.0, v126, 2.0
	v_mul_f32_e32 v131, v130, v129
	v_fma_f32 v132, -v128, v131, v130
	v_fmac_f32_e32 v131, v132, v129
	v_fma_f32 v128, -v128, v131, v130
	v_div_fmas_f32 v128, v128, v129, v131
	v_div_fixup_f32 v126, v128, v126, 2.0
	v_sub_f32_e32 v126, 1.0, v126
	v_add_f32_e32 v126, 1.0, v126
	v_mul_f32_e32 v104, v127, v126
	v_add_f32_e32 v126, v84, v100
	v_mul_f32_e32 v104, v104, v126
	v_bfe_u32 v126, v104, 16, 1
	v_add3_u32 v104, v104, v126, s27
	global_store_short_d16_hi v124, v104, s[54:55]
	v_mul_f32_e32 v126, 0x3d372713, v105
	v_mul_f32_e32 v126, v105, v126
	v_fma_f32 v126, v105, v126, v105
	v_mul_f32_e32 v126, 0x3f4c422a, v126
	v_add_f32_e32 v126, v126, v126
	v_mul_f32_e32 v126, 0x3fb8aa3b, v126
	v_exp_f32_e32 v126, v126
	v_mul_f32_e32 v127, 0.5, v105
	v_add_f32_e32 v126, 1.0, v126
	v_div_scale_f32 v128, s[100:101], v126, v126, 2.0
	v_rcp_f32_e32 v129, v128
	s_nop 0
	v_fma_f32 v130, -v128, v129, 1.0
	v_fmac_f32_e32 v129, v130, v129
	v_div_scale_f32 v130, vcc, 2.0, v126, 2.0
	v_mul_f32_e32 v131, v130, v129
	v_fma_f32 v132, -v128, v131, v130
	v_fmac_f32_e32 v131, v132, v129
	v_fma_f32 v128, -v128, v131, v130
	v_div_fmas_f32 v128, v128, v129, v131
	v_div_fixup_f32 v126, v128, v126, 2.0
	v_sub_f32_e32 v126, 1.0, v126
	v_add_f32_e32 v126, 1.0, v126
	v_mul_f32_e32 v105, v127, v126
	v_add_f32_e32 v126, v88, v100
	v_mul_f32_e32 v105, v105, v126
	v_bfe_u32 v126, v105, 16, 1
	v_add3_u32 v105, v105, v126, s27
	global_store_short_d16_hi v124, v105, s[54:55] offset:32
	v_mul_f32_e32 v126, 0x3d372713, v106
	v_mul_f32_e32 v126, v106, v126
	v_fma_f32 v126, v106, v126, v106
	v_mul_f32_e32 v126, 0x3f4c422a, v126
	v_add_f32_e32 v126, v126, v126
	v_mul_f32_e32 v126, 0x3fb8aa3b, v126
	v_exp_f32_e32 v126, v126
	v_mul_f32_e32 v127, 0.5, v106
	v_add_f32_e32 v126, 1.0, v126
	v_div_scale_f32 v128, s[100:101], v126, v126, 2.0
	v_rcp_f32_e32 v129, v128
	s_nop 0
	v_fma_f32 v130, -v128, v129, 1.0
	v_fmac_f32_e32 v129, v130, v129
	v_div_scale_f32 v130, vcc, 2.0, v126, 2.0
	v_mul_f32_e32 v131, v130, v129
	v_fma_f32 v132, -v128, v131, v130
	v_fmac_f32_e32 v131, v132, v129
	v_fma_f32 v128, -v128, v131, v130
	v_div_fmas_f32 v128, v128, v129, v131
	v_div_fixup_f32 v126, v128, v126, 2.0
	v_sub_f32_e32 v126, 1.0, v126
	v_add_f32_e32 v126, 1.0, v126
	v_mul_f32_e32 v106, v127, v126
	v_add_f32_e32 v126, v92, v100
	v_mul_f32_e32 v106, v106, v126
	v_bfe_u32 v126, v106, 16, 1
	v_add3_u32 v106, v106, v126, s27
	global_store_short_d16_hi v124, v106, s[54:55] offset:64
	v_mul_f32_e32 v126, 0x3d372713, v107
	v_mul_f32_e32 v126, v107, v126
	v_fma_f32 v126, v107, v126, v107
	v_mul_f32_e32 v126, 0x3f4c422a, v126
	v_add_f32_e32 v126, v126, v126
	v_mul_f32_e32 v126, 0x3fb8aa3b, v126
	v_exp_f32_e32 v126, v126
	v_mul_f32_e32 v127, 0.5, v107
	v_add_f32_e32 v126, 1.0, v126
	v_div_scale_f32 v128, s[100:101], v126, v126, 2.0
	v_rcp_f32_e32 v129, v128
	s_nop 0
	v_fma_f32 v130, -v128, v129, 1.0
	v_fmac_f32_e32 v129, v130, v129
	v_div_scale_f32 v130, vcc, 2.0, v126, 2.0
	v_mul_f32_e32 v131, v130, v129
	v_fma_f32 v132, -v128, v131, v130
	v_fmac_f32_e32 v131, v132, v129
	v_fma_f32 v128, -v128, v131, v130
	v_div_fmas_f32 v128, v128, v129, v131
	v_div_fixup_f32 v126, v128, v126, 2.0
	v_sub_f32_e32 v126, 1.0, v126
	v_add_f32_e32 v126, 1.0, v126
	v_mul_f32_e32 v107, v127, v126
	v_add_f32_e32 v126, v96, v100
	v_mul_f32_e32 v107, v107, v126
	v_bfe_u32 v126, v107, 16, 1
	v_add3_u32 v107, v107, v126, s27
	global_store_short_d16_hi v124, v107, s[54:55] offset:96
	v_add_u32_e32 v125, 0x800, v124
	v_mul_f32_e32 v126, 0x3d372713, v108
	v_mul_f32_e32 v126, v108, v126
	v_fma_f32 v126, v108, v126, v108
	v_mul_f32_e32 v126, 0x3f4c422a, v126
	v_add_f32_e32 v126, v126, v126
	v_mul_f32_e32 v126, 0x3fb8aa3b, v126
	v_exp_f32_e32 v126, v126
	v_mul_f32_e32 v127, 0.5, v108
	v_add_f32_e32 v126, 1.0, v126
	v_div_scale_f32 v128, s[100:101], v126, v126, 2.0
	v_rcp_f32_e32 v129, v128
	s_nop 0
	v_fma_f32 v130, -v128, v129, 1.0
	v_fmac_f32_e32 v129, v130, v129
	v_div_scale_f32 v130, vcc, 2.0, v126, 2.0
	v_mul_f32_e32 v131, v130, v129
	v_fma_f32 v132, -v128, v131, v130
	v_fmac_f32_e32 v131, v132, v129
	v_fma_f32 v128, -v128, v131, v130
	v_div_fmas_f32 v128, v128, v129, v131
	v_div_fixup_f32 v126, v128, v126, 2.0
	v_sub_f32_e32 v126, 1.0, v126
	v_add_f32_e32 v126, 1.0, v126
	v_mul_f32_e32 v108, v127, v126
	v_add_f32_e32 v126, v85, v101
	v_mul_f32_e32 v108, v108, v126
	v_bfe_u32 v126, v108, 16, 1
	v_add3_u32 v108, v108, v126, s27
	global_store_short_d16_hi v125, v108, s[54:55]
	v_mul_f32_e32 v126, 0x3d372713, v109
	v_mul_f32_e32 v126, v109, v126
	v_fma_f32 v126, v109, v126, v109
	v_mul_f32_e32 v126, 0x3f4c422a, v126
	v_add_f32_e32 v126, v126, v126
	v_mul_f32_e32 v126, 0x3fb8aa3b, v126
	v_exp_f32_e32 v126, v126
	v_mul_f32_e32 v127, 0.5, v109
	v_add_f32_e32 v126, 1.0, v126
	v_div_scale_f32 v128, s[100:101], v126, v126, 2.0
	v_rcp_f32_e32 v129, v128
	s_nop 0
	v_fma_f32 v130, -v128, v129, 1.0
	v_fmac_f32_e32 v129, v130, v129
	v_div_scale_f32 v130, vcc, 2.0, v126, 2.0
	v_mul_f32_e32 v131, v130, v129
	v_fma_f32 v132, -v128, v131, v130
	v_fmac_f32_e32 v131, v132, v129
	v_fma_f32 v128, -v128, v131, v130
	v_div_fmas_f32 v128, v128, v129, v131
	v_div_fixup_f32 v126, v128, v126, 2.0
	v_sub_f32_e32 v126, 1.0, v126
	v_add_f32_e32 v126, 1.0, v126
	v_mul_f32_e32 v109, v127, v126
	v_add_f32_e32 v126, v89, v101
	v_mul_f32_e32 v109, v109, v126
	v_bfe_u32 v126, v109, 16, 1
	v_add3_u32 v109, v109, v126, s27
	global_store_short_d16_hi v125, v109, s[54:55] offset:32
	v_mul_f32_e32 v126, 0x3d372713, v110
	v_mul_f32_e32 v126, v110, v126
	v_fma_f32 v126, v110, v126, v110
	v_mul_f32_e32 v126, 0x3f4c422a, v126
	v_add_f32_e32 v126, v126, v126
	v_mul_f32_e32 v126, 0x3fb8aa3b, v126
	v_exp_f32_e32 v126, v126
	v_mul_f32_e32 v127, 0.5, v110
	v_add_f32_e32 v126, 1.0, v126
	v_div_scale_f32 v128, s[100:101], v126, v126, 2.0
	v_rcp_f32_e32 v129, v128
	s_nop 0
	v_fma_f32 v130, -v128, v129, 1.0
	v_fmac_f32_e32 v129, v130, v129
	v_div_scale_f32 v130, vcc, 2.0, v126, 2.0
	v_mul_f32_e32 v131, v130, v129
	v_fma_f32 v132, -v128, v131, v130
	v_fmac_f32_e32 v131, v132, v129
	v_fma_f32 v128, -v128, v131, v130
	v_div_fmas_f32 v128, v128, v129, v131
	v_div_fixup_f32 v126, v128, v126, 2.0
	v_sub_f32_e32 v126, 1.0, v126
	v_add_f32_e32 v126, 1.0, v126
	v_mul_f32_e32 v110, v127, v126
	v_add_f32_e32 v126, v93, v101
	v_mul_f32_e32 v110, v110, v126
	v_bfe_u32 v126, v110, 16, 1
	v_add3_u32 v110, v110, v126, s27
	global_store_short_d16_hi v125, v110, s[54:55] offset:64
	v_mul_f32_e32 v126, 0x3d372713, v111
	v_mul_f32_e32 v126, v111, v126
	v_fma_f32 v126, v111, v126, v111
	v_mul_f32_e32 v126, 0x3f4c422a, v126
	v_add_f32_e32 v126, v126, v126
	v_mul_f32_e32 v126, 0x3fb8aa3b, v126
	v_exp_f32_e32 v126, v126
	v_mul_f32_e32 v127, 0.5, v111
	v_add_f32_e32 v126, 1.0, v126
	v_div_scale_f32 v128, s[100:101], v126, v126, 2.0
	v_rcp_f32_e32 v129, v128
	s_nop 0
	v_fma_f32 v130, -v128, v129, 1.0
	v_fmac_f32_e32 v129, v130, v129
	v_div_scale_f32 v130, vcc, 2.0, v126, 2.0
	v_mul_f32_e32 v131, v130, v129
	v_fma_f32 v132, -v128, v131, v130
	v_fmac_f32_e32 v131, v132, v129
	v_fma_f32 v128, -v128, v131, v130
	v_div_fmas_f32 v128, v128, v129, v131
	v_div_fixup_f32 v126, v128, v126, 2.0
	v_sub_f32_e32 v126, 1.0, v126
	v_add_f32_e32 v126, 1.0, v126
	v_mul_f32_e32 v111, v127, v126
	v_add_f32_e32 v126, v97, v101
	v_mul_f32_e32 v111, v111, v126
	v_bfe_u32 v126, v111, 16, 1
	v_add3_u32 v111, v111, v126, s27
	global_store_short_d16_hi v125, v111, s[54:55] offset:96
	v_add_u32_e32 v125, 0x1000, v124
	v_mul_f32_e32 v126, 0x3d372713, v112
	v_mul_f32_e32 v126, v112, v126
	v_fma_f32 v126, v112, v126, v112
	v_mul_f32_e32 v126, 0x3f4c422a, v126
	v_add_f32_e32 v126, v126, v126
	v_mul_f32_e32 v126, 0x3fb8aa3b, v126
	v_exp_f32_e32 v126, v126
	v_mul_f32_e32 v127, 0.5, v112
	v_add_f32_e32 v126, 1.0, v126
	v_div_scale_f32 v128, s[100:101], v126, v126, 2.0
	v_rcp_f32_e32 v129, v128
	s_nop 0
	v_fma_f32 v130, -v128, v129, 1.0
	v_fmac_f32_e32 v129, v130, v129
	v_div_scale_f32 v130, vcc, 2.0, v126, 2.0
	v_mul_f32_e32 v131, v130, v129
	v_fma_f32 v132, -v128, v131, v130
	v_fmac_f32_e32 v131, v132, v129
	v_fma_f32 v128, -v128, v131, v130
	v_div_fmas_f32 v128, v128, v129, v131
	v_div_fixup_f32 v126, v128, v126, 2.0
	v_sub_f32_e32 v126, 1.0, v126
	v_add_f32_e32 v126, 1.0, v126
	v_mul_f32_e32 v112, v127, v126
	v_add_f32_e32 v126, v86, v102
	v_mul_f32_e32 v112, v112, v126
	v_bfe_u32 v126, v112, 16, 1
	v_add3_u32 v112, v112, v126, s27
	global_store_short_d16_hi v125, v112, s[54:55]
	v_mul_f32_e32 v126, 0x3d372713, v113
	v_mul_f32_e32 v126, v113, v126
	v_fma_f32 v126, v113, v126, v113
	v_mul_f32_e32 v126, 0x3f4c422a, v126
	v_add_f32_e32 v126, v126, v126
	v_mul_f32_e32 v126, 0x3fb8aa3b, v126
	v_exp_f32_e32 v126, v126
	v_mul_f32_e32 v127, 0.5, v113
	v_add_f32_e32 v126, 1.0, v126
	v_div_scale_f32 v128, s[100:101], v126, v126, 2.0
	v_rcp_f32_e32 v129, v128
	s_nop 0
	v_fma_f32 v130, -v128, v129, 1.0
	v_fmac_f32_e32 v129, v130, v129
	v_div_scale_f32 v130, vcc, 2.0, v126, 2.0
	v_mul_f32_e32 v131, v130, v129
	v_fma_f32 v132, -v128, v131, v130
	v_fmac_f32_e32 v131, v132, v129
	v_fma_f32 v128, -v128, v131, v130
	v_div_fmas_f32 v128, v128, v129, v131
	v_div_fixup_f32 v126, v128, v126, 2.0
	v_sub_f32_e32 v126, 1.0, v126
	v_add_f32_e32 v126, 1.0, v126
	v_mul_f32_e32 v113, v127, v126
	v_add_f32_e32 v126, v90, v102
	v_mul_f32_e32 v113, v113, v126
	v_bfe_u32 v126, v113, 16, 1
	v_add3_u32 v113, v113, v126, s27
	global_store_short_d16_hi v125, v113, s[54:55] offset:32
	v_mul_f32_e32 v126, 0x3d372713, v114
	v_mul_f32_e32 v126, v114, v126
	v_fma_f32 v126, v114, v126, v114
	v_mul_f32_e32 v126, 0x3f4c422a, v126
	v_add_f32_e32 v126, v126, v126
	v_mul_f32_e32 v126, 0x3fb8aa3b, v126
	v_exp_f32_e32 v126, v126
	v_mul_f32_e32 v127, 0.5, v114
	v_add_f32_e32 v126, 1.0, v126
	v_div_scale_f32 v128, s[100:101], v126, v126, 2.0
	v_rcp_f32_e32 v129, v128
	s_nop 0
	v_fma_f32 v130, -v128, v129, 1.0
	v_fmac_f32_e32 v129, v130, v129
	v_div_scale_f32 v130, vcc, 2.0, v126, 2.0
	v_mul_f32_e32 v131, v130, v129
	v_fma_f32 v132, -v128, v131, v130
	v_fmac_f32_e32 v131, v132, v129
	v_fma_f32 v128, -v128, v131, v130
	v_div_fmas_f32 v128, v128, v129, v131
	v_div_fixup_f32 v126, v128, v126, 2.0
	v_sub_f32_e32 v126, 1.0, v126
	v_add_f32_e32 v126, 1.0, v126
	v_mul_f32_e32 v114, v127, v126
	v_add_f32_e32 v126, v94, v102
	v_mul_f32_e32 v114, v114, v126
	v_bfe_u32 v126, v114, 16, 1
	v_add3_u32 v114, v114, v126, s27
	global_store_short_d16_hi v125, v114, s[54:55] offset:64
	v_mul_f32_e32 v126, 0x3d372713, v115
	v_mul_f32_e32 v126, v115, v126
	v_fma_f32 v126, v115, v126, v115
	v_mul_f32_e32 v126, 0x3f4c422a, v126
	v_add_f32_e32 v126, v126, v126
	v_mul_f32_e32 v126, 0x3fb8aa3b, v126
	v_exp_f32_e32 v126, v126
	v_mul_f32_e32 v127, 0.5, v115
	v_add_f32_e32 v126, 1.0, v126
	v_div_scale_f32 v128, s[100:101], v126, v126, 2.0
	v_rcp_f32_e32 v129, v128
	s_nop 0
	v_fma_f32 v130, -v128, v129, 1.0
	v_fmac_f32_e32 v129, v130, v129
	v_div_scale_f32 v130, vcc, 2.0, v126, 2.0
	v_mul_f32_e32 v131, v130, v129
	v_fma_f32 v132, -v128, v131, v130
	v_fmac_f32_e32 v131, v132, v129
	v_fma_f32 v128, -v128, v131, v130
	v_div_fmas_f32 v128, v128, v129, v131
	v_div_fixup_f32 v126, v128, v126, 2.0
	v_sub_f32_e32 v126, 1.0, v126
	v_add_f32_e32 v126, 1.0, v126
	v_mul_f32_e32 v115, v127, v126
	v_add_f32_e32 v126, v98, v102
	v_mul_f32_e32 v115, v115, v126
	v_bfe_u32 v126, v115, 16, 1
	v_add3_u32 v115, v115, v126, s27
	global_store_short_d16_hi v125, v115, s[54:55] offset:96
	v_add_u32_e32 v125, 0x1800, v124
	v_mul_f32_e32 v126, 0x3d372713, v116
	v_mul_f32_e32 v126, v116, v126
	v_fma_f32 v126, v116, v126, v116
	v_mul_f32_e32 v126, 0x3f4c422a, v126
	v_add_f32_e32 v126, v126, v126
	v_mul_f32_e32 v126, 0x3fb8aa3b, v126
	v_exp_f32_e32 v126, v126
	v_mul_f32_e32 v127, 0.5, v116
	v_add_f32_e32 v126, 1.0, v126
	v_div_scale_f32 v128, s[100:101], v126, v126, 2.0
	v_rcp_f32_e32 v129, v128
	s_nop 0
	v_fma_f32 v130, -v128, v129, 1.0
	v_fmac_f32_e32 v129, v130, v129
	v_div_scale_f32 v130, vcc, 2.0, v126, 2.0
	v_mul_f32_e32 v131, v130, v129
	v_fma_f32 v132, -v128, v131, v130
	v_fmac_f32_e32 v131, v132, v129
	v_fma_f32 v128, -v128, v131, v130
	v_div_fmas_f32 v128, v128, v129, v131
	v_div_fixup_f32 v126, v128, v126, 2.0
	v_sub_f32_e32 v126, 1.0, v126
	v_add_f32_e32 v126, 1.0, v126
	v_mul_f32_e32 v116, v127, v126
	v_add_f32_e32 v126, v87, v103
	v_mul_f32_e32 v116, v116, v126
	v_bfe_u32 v126, v116, 16, 1
	v_add3_u32 v116, v116, v126, s27
	global_store_short_d16_hi v125, v116, s[54:55]
	v_mul_f32_e32 v126, 0x3d372713, v117
	v_mul_f32_e32 v126, v117, v126
	v_fma_f32 v126, v117, v126, v117
	v_mul_f32_e32 v126, 0x3f4c422a, v126
	v_add_f32_e32 v126, v126, v126
	v_mul_f32_e32 v126, 0x3fb8aa3b, v126
	v_exp_f32_e32 v126, v126
	v_mul_f32_e32 v127, 0.5, v117
	v_add_f32_e32 v126, 1.0, v126
	v_div_scale_f32 v128, s[100:101], v126, v126, 2.0
	v_rcp_f32_e32 v129, v128
	s_nop 0
	v_fma_f32 v130, -v128, v129, 1.0
	v_fmac_f32_e32 v129, v130, v129
	v_div_scale_f32 v130, vcc, 2.0, v126, 2.0
	v_mul_f32_e32 v131, v130, v129
	v_fma_f32 v132, -v128, v131, v130
	v_fmac_f32_e32 v131, v132, v129
	v_fma_f32 v128, -v128, v131, v130
	v_div_fmas_f32 v128, v128, v129, v131
	v_div_fixup_f32 v126, v128, v126, 2.0
	v_sub_f32_e32 v126, 1.0, v126
	v_add_f32_e32 v126, 1.0, v126
	v_mul_f32_e32 v117, v127, v126
	v_add_f32_e32 v126, v91, v103
	v_mul_f32_e32 v117, v117, v126
	v_bfe_u32 v126, v117, 16, 1
	v_add3_u32 v117, v117, v126, s27
	global_store_short_d16_hi v125, v117, s[54:55] offset:32
	v_mul_f32_e32 v126, 0x3d372713, v118
	v_mul_f32_e32 v126, v118, v126
	v_fma_f32 v126, v118, v126, v118
	v_mul_f32_e32 v126, 0x3f4c422a, v126
	v_add_f32_e32 v126, v126, v126
	v_mul_f32_e32 v126, 0x3fb8aa3b, v126
	v_exp_f32_e32 v126, v126
	v_mul_f32_e32 v127, 0.5, v118
	v_add_f32_e32 v126, 1.0, v126
	v_div_scale_f32 v128, s[100:101], v126, v126, 2.0
	v_rcp_f32_e32 v129, v128
	s_nop 0
	v_fma_f32 v130, -v128, v129, 1.0
	v_fmac_f32_e32 v129, v130, v129
	v_div_scale_f32 v130, vcc, 2.0, v126, 2.0
	v_mul_f32_e32 v131, v130, v129
	v_fma_f32 v132, -v128, v131, v130
	v_fmac_f32_e32 v131, v132, v129
	v_fma_f32 v128, -v128, v131, v130
	v_div_fmas_f32 v128, v128, v129, v131
	v_div_fixup_f32 v126, v128, v126, 2.0
	v_sub_f32_e32 v126, 1.0, v126
	v_add_f32_e32 v126, 1.0, v126
	v_mul_f32_e32 v118, v127, v126
	v_add_f32_e32 v126, v95, v103
	v_mul_f32_e32 v118, v118, v126
	v_bfe_u32 v126, v118, 16, 1
	v_add3_u32 v118, v118, v126, s27
	global_store_short_d16_hi v125, v118, s[54:55] offset:64
	v_mul_f32_e32 v126, 0x3d372713, v119
	v_mul_f32_e32 v126, v119, v126
	v_fma_f32 v126, v119, v126, v119
	v_mul_f32_e32 v126, 0x3f4c422a, v126
	v_add_f32_e32 v126, v126, v126
	v_mul_f32_e32 v126, 0x3fb8aa3b, v126
	v_exp_f32_e32 v126, v126
	v_mul_f32_e32 v127, 0.5, v119
	v_add_f32_e32 v126, 1.0, v126
	v_div_scale_f32 v128, s[100:101], v126, v126, 2.0
	v_rcp_f32_e32 v129, v128
	s_nop 0
	v_fma_f32 v130, -v128, v129, 1.0
	v_fmac_f32_e32 v129, v130, v129
	v_div_scale_f32 v130, vcc, 2.0, v126, 2.0
	v_mul_f32_e32 v131, v130, v129
	v_fma_f32 v132, -v128, v131, v130
	v_fmac_f32_e32 v131, v132, v129
	v_fma_f32 v128, -v128, v131, v130
	v_div_fmas_f32 v128, v128, v129, v131
	v_div_fixup_f32 v126, v128, v126, 2.0
	v_sub_f32_e32 v126, 1.0, v126
	v_add_f32_e32 v126, 1.0, v126
	v_mul_f32_e32 v119, v127, v126
	v_add_f32_e32 v126, v99, v103
	v_mul_f32_e32 v119, v119, v126
	v_bfe_u32 v126, v119, 16, 1
	v_add3_u32 v119, v119, v126, s27
	global_store_short_d16_hi v125, v119, s[54:55] offset:96
	s_branch .Lsp3_e2
